# prep: mem f32->bf16 conversion loop with four grid-stride loads in flight per pass (was one load per iteration with a full wait)
# speedup vs baseline: 1.0202x; 1.0045x over previous
; __device__ __forceinline__ unsigned cvt_pk_bf16(float lo, float hi) { const f32x2v v = {lo, hi}; const b16x2v r = __builtin_convertvector(v, b16x2v); return __builtin_bit_cast(unsigned, r); }
; __device__ void prep_phase(const Params& p, unsigned char* smem_g) {
;     ...
;     { bf16_t* mb = (bf16_t*)(ws + OFF_MEMB);
;       for (int e = blockIdx.x * 512 + tid; e < 1024 * 2048 / 4; e += gridDim.x * 512) { const f32x4 v = *(const f32x4*)(p.mem + (size_t)e * 4); u32x2 w; w.x = cvt_pk_bf16(v[0], v[1]); w.y = cvt_pk_bf16(v[2], v[3]); *(u32x2*)(mb + (size_t)e * 4) = w; } }
.LBB0_148:
	s_or_b64 exec, exec, s[0:1]
	v_readlane_b32 s6, v251, 37
	v_readlane_b32 s7, v251, 38
	v_cmp_gt_i32_e32 vcc, s11, v0
	s_and_saveexec_b64 s[0:1], vcc
	s_cbranch_execz .LBB0_151
	s_mov_b64 s[2:3], 0
	s_mov_b32 s4, 0x80000
	v_mov_b32_e32 v11, 0x7ffff
.LBB0_150:
	v_add_u32_e32 v8, s70, v0
	v_add_u32_e32 v9, s70, v8
	v_add_u32_e32 v10, s70, v9
	v_min_i32_e32 v12, v8, v11
	v_min_i32_e32 v13, v9, v11
	v_min_i32_e32 v14, v10, v11
	v_lshlrev_b32_e32 v28, 4, v0
	v_lshlrev_b32_e32 v29, 4, v12
	v_lshlrev_b32_e32 v30, 4, v13
	v_lshlrev_b32_e32 v31, 4, v14
	global_load_dwordx4 v[4:7], v28, s[74:75]
	global_load_dwordx4 v[16:19], v29, s[74:75]
	global_load_dwordx4 v[20:23], v30, s[74:75]
	global_load_dwordx4 v[24:27], v31, s[74:75]
	v_lshlrev_b32_e32 v28, 3, v0
	v_lshlrev_b32_e32 v29, 3, v8
	v_lshlrev_b32_e32 v30, 3, v9
	v_lshlrev_b32_e32 v31, 3, v10
	s_mov_b64 s[8:9], exec
	s_waitcnt vmcnt(3)
	v_cvt_pk_bf16_f32 v4, v4, v5
	v_cvt_pk_bf16_f32 v5, v6, v7
	global_store_dwordx2 v28, v[4:5], s[6:7]
	s_waitcnt vmcnt(0)
	v_cvt_pk_bf16_f32 v16, v16, v17
	v_cvt_pk_bf16_f32 v17, v18, v19
	v_cvt_pk_bf16_f32 v20, v20, v21
	v_cvt_pk_bf16_f32 v21, v22, v23
	v_cvt_pk_bf16_f32 v24, v24, v25
	v_cvt_pk_bf16_f32 v25, v26, v27
	v_cmp_gt_i32_e32 vcc, s4, v8
	s_and_b64 exec, exec, vcc
	global_store_dwordx2 v29, v[16:17], s[6:7]
	v_cmp_gt_i32_e32 vcc, s4, v9
	s_and_b64 exec, exec, vcc
	global_store_dwordx2 v30, v[20:21], s[6:7]
	v_cmp_gt_i32_e32 vcc, s4, v10
	s_and_b64 exec, exec, vcc
	global_store_dwordx2 v31, v[24:25], s[6:7]
	s_mov_b64 exec, s[8:9]
	v_add_u32_e32 v0, s70, v10
	v_cmp_le_i32_e32 vcc, s4, v0
	s_or_b64 s[2:3], vcc, s[2:3]
	s_andn2_b64 exec, exec, s[2:3]
	s_cbranch_execnz .LBB0_150
